# P2 attention block epilogue pipelined: 5 rows of z loads in flight, DPP lane exchange instead of ds_bpermute, no per-element vmcnt(0); P7: transposed o tile stored as 2 dwordx2, M waves sleep 640 cyc
# speedup vs baseline: 1.0447x; 1.0447x over previous
; #define SBAR() __builtin_amdgcn_sched_barrier(0)
; __device__ __forceinline__ int crow(int r, int hi) { return (r & 3) + 8 * (r >> 2) + 4 * hi; }
; #define SEAM_K0() do { VMWN(NQL); if constexpr (F32) { SWRITE_KF(0); SBAR(); SLOAD_F((const float*)nxt.V, kbn); } else { SWRITE_HK(0); } SBAR(); } while (0)
; template <class TIn, class TOut>
; __device__ __forceinline__ void causal_swa_block(const BlockRef<TIn, TOut>& cur, const BlockRef<TIn, TOut>& nxt, int skv, int W, char* lds, Seam<TIn>& S, float TH, float TH2, int wave_s) {
;     ...
;     SBAR(); SEAM_K0();
;     if (hi == 0) li_l[r32] = l_reg; asm volatile("s_waitcnt lgkmcnt(0)" ::: "memory");
;     float rli[16];
; #pragma unroll
;     for (int r = 0; r < 16; ++r) rli[r] = __builtin_amdgcn_rcpf(li_l[crow(r, hi)]);
;     int eo = (wid * QBLK + 4 * hi) * OSTR + r32; asm volatile("" : "+v"(eo));
;     TOut* Ow = cur.O + eo; const TOut* Zw = cur.Z + eo;
; #pragma unroll
;     for (int r = 0; r < 16; ++r) { const int orow = ((r & 3) + 8 * (r >> 2)) * OSTR;
; #pragma unroll
;         for (int d0 = 0; d0 < 4; ++d0) { const float v = o[d0][r] * rli[r] * __bfloat162float(Zw[orow + d0 * 32]);
;             if constexpr (same_t<TOut, float>::v) { Ow[orow + d0 * 32] = v; }
;             else { const float vn = __shfl_xor(v, 1);
;                    if ((r32 & 1) == 0) *(unsigned*)(Ow + orow + d0 * 32) = cvtpk(v, vn); } } }
.LBB0_505:
	s_waitcnt vmcnt(8)
	s_waitcnt vmcnt(9)
	ds_write_b128 v214, v[96:99] offset:32768
	s_waitcnt vmcnt(8)
	ds_write_b128 v214, v[104:107] offset:40960
	v_cmp_gt_u32_e32 vcc, 32, v215
	s_and_saveexec_b64 s[2:3], vcc
	ds_write_b32 v217, v112
	s_or_b64 exec, exec, s[2:3]
	v_or_b32_e32 v80, s21, v213
	s_waitcnt lgkmcnt(0)
	v_lshl_or_b32 v80, v80, 11, v212
	ds_read_b128 v[76:79], v216
	ds_read_b128 v[72:75], v216 offset:32
	ds_read_b128 v[68:71], v216 offset:64
	ds_read_b128 v[64:67], v216 offset:96
	v_and_b32_e32 v84, 1, v211
	v_lshlrev_b32_e32 v80, 1, v80
	v_cmp_eq_u32_e64 s[2:3], 0, v84
	v_mov_b32_e32 v81, v80
	global_load_ushort v84, v81, s[28:29]
	global_load_ushort v85, v81, s[28:29] offset:64
	global_load_ushort v86, v81, s[28:29] offset:128
	global_load_ushort v87, v81, s[28:29] offset:192
	v_add_u32_e32 v81, 0x1000, v80
	global_load_ushort v88, v81, s[28:29]
	global_load_ushort v89, v81, s[28:29] offset:64
	global_load_ushort v90, v81, s[28:29] offset:128
	global_load_ushort v91, v81, s[28:29] offset:192
	v_add_u32_e32 v81, 0x2000, v80
	global_load_ushort v92, v81, s[28:29]
	global_load_ushort v93, v81, s[28:29] offset:64
	global_load_ushort v94, v81, s[28:29] offset:128
	global_load_ushort v95, v81, s[28:29] offset:192
	v_add_u32_e32 v81, 0x3000, v80
	global_load_ushort v96, v81, s[28:29]
	global_load_ushort v97, v81, s[28:29] offset:64
	global_load_ushort v98, v81, s[28:29] offset:128
	global_load_ushort v99, v81, s[28:29] offset:192
	v_add_u32_e32 v81, 0x8000, v80
	global_load_ushort v104, v81, s[28:29]
	global_load_ushort v105, v81, s[28:29] offset:64
	global_load_ushort v106, v81, s[28:29] offset:128
	global_load_ushort v107, v81, s[28:29] offset:192
	s_waitcnt lgkmcnt(0)
	v_rcp_f32_e32 v76, v76
	v_rcp_f32_e32 v77, v77
	v_rcp_f32_e32 v78, v78
	v_rcp_f32_e32 v79, v79
	v_rcp_f32_e32 v72, v72
	v_rcp_f32_e32 v73, v73
	v_rcp_f32_e32 v74, v74
	v_rcp_f32_e32 v75, v75
	v_rcp_f32_e32 v68, v68
	v_rcp_f32_e32 v69, v69
	v_rcp_f32_e32 v70, v70
	v_rcp_f32_e32 v71, v71
	v_rcp_f32_e32 v64, v64
	v_rcp_f32_e32 v65, v65
	v_rcp_f32_e32 v66, v66
	v_rcp_f32_e32 v67, v67
	s_waitcnt vmcnt(16)
	v_mul_f32_e32 v48, v48, v76
	v_mul_f32_e32 v32, v32, v76
	v_mul_f32_e32 v16, v16, v76
	v_mul_f32_e32 v0, v0, v76
	v_lshlrev_b32_e32 v84, 16, v84
	v_lshlrev_b32_e32 v85, 16, v85
	v_lshlrev_b32_e32 v86, 16, v86
	v_lshlrev_b32_e32 v87, 16, v87
	v_mul_f32_e32 v48, v48, v84
	v_mul_f32_e32 v32, v32, v85
	v_mul_f32_e32 v16, v16, v86
	v_mul_f32_e32 v0, v0, v87
	v_mov_b32_dpp v84, v48 quad_perm:[1,0,3,2] row_mask:0xf bank_mask:0xf
	v_mov_b32_dpp v85, v32 quad_perm:[1,0,3,2] row_mask:0xf bank_mask:0xf
	v_mov_b32_dpp v86, v16 quad_perm:[1,0,3,2] row_mask:0xf bank_mask:0xf
	v_mov_b32_dpp v87, v0 quad_perm:[1,0,3,2] row_mask:0xf bank_mask:0xf
	v_cvt_pk_bf16_f32 v48, v48, v84
	v_cvt_pk_bf16_f32 v32, v32, v85
	v_cvt_pk_bf16_f32 v16, v16, v86
	v_cvt_pk_bf16_f32 v0, v0, v87
	v_mov_b32_e32 v82, v80
	s_and_saveexec_b64 s[4:5], s[2:3]
	global_store_dword v82, v48, s[66:67]
	global_store_dword v82, v32, s[66:67] offset:64
	global_store_dword v82, v16, s[66:67] offset:128
	global_store_dword v82, v0, s[66:67] offset:192
	s_or_b64 exec, exec, s[4:5]
	v_add_u32_e32 v81, 0x9000, v80
	global_load_ushort v84, v81, s[28:29]
	global_load_ushort v85, v81, s[28:29] offset:64
	global_load_ushort v86, v81, s[28:29] offset:128
	global_load_ushort v87, v81, s[28:29] offset:192
	s_waitcnt vmcnt(20)
	v_mul_f32_e32 v49, v49, v77
	v_mul_f32_e32 v33, v33, v77
	v_mul_f32_e32 v17, v17, v77
	v_mul_f32_e32 v1, v1, v77
	v_lshlrev_b32_e32 v88, 16, v88
	v_lshlrev_b32_e32 v89, 16, v89
	v_lshlrev_b32_e32 v90, 16, v90
	v_lshlrev_b32_e32 v91, 16, v91
	v_mul_f32_e32 v49, v49, v88
	v_mul_f32_e32 v33, v33, v89
	v_mul_f32_e32 v17, v17, v90
	v_mul_f32_e32 v1, v1, v91
	v_mov_b32_dpp v88, v49 quad_perm:[1,0,3,2] row_mask:0xf bank_mask:0xf
	v_mov_b32_dpp v89, v33 quad_perm:[1,0,3,2] row_mask:0xf bank_mask:0xf
	v_mov_b32_dpp v90, v17 quad_perm:[1,0,3,2] row_mask:0xf bank_mask:0xf
	v_mov_b32_dpp v91, v1 quad_perm:[1,0,3,2] row_mask:0xf bank_mask:0xf
	v_cvt_pk_bf16_f32 v49, v49, v88
	v_cvt_pk_bf16_f32 v33, v33, v89
	v_cvt_pk_bf16_f32 v17, v17, v90
	v_cvt_pk_bf16_f32 v1, v1, v91
	v_add_u32_e32 v82, 0x1000, v80
	s_and_saveexec_b64 s[4:5], s[2:3]
	global_store_dword v82, v49, s[66:67]
	global_store_dword v82, v33, s[66:67] offset:64
	global_store_dword v82, v17, s[66:67] offset:128
	global_store_dword v82, v1, s[66:67] offset:192
	s_or_b64 exec, exec, s[4:5]
	v_add_u32_e32 v81, 0xa000, v80
	global_load_ushort v88, v81, s[28:29]
	global_load_ushort v89, v81, s[28:29] offset:64
	global_load_ushort v90, v81, s[28:29] offset:128
	global_load_ushort v91, v81, s[28:29] offset:192
	s_waitcnt vmcnt(24)
	v_mul_f32_e32 v50, v50, v78
	v_mul_f32_e32 v34, v34, v78
	v_mul_f32_e32 v18, v18, v78
	v_mul_f32_e32 v2, v2, v78
	v_lshlrev_b32_e32 v92, 16, v92
	v_lshlrev_b32_e32 v93, 16, v93
	v_lshlrev_b32_e32 v94, 16, v94
	v_lshlrev_b32_e32 v95, 16, v95
	v_mul_f32_e32 v50, v50, v92
	v_mul_f32_e32 v34, v34, v93
	v_mul_f32_e32 v18, v18, v94
	v_mul_f32_e32 v2, v2, v95
	v_mov_b32_dpp v92, v50 quad_perm:[1,0,3,2] row_mask:0xf bank_mask:0xf
	v_mov_b32_dpp v93, v34 quad_perm:[1,0,3,2] row_mask:0xf bank_mask:0xf
	v_mov_b32_dpp v94, v18 quad_perm:[1,0,3,2] row_mask:0xf bank_mask:0xf
	v_mov_b32_dpp v95, v2 quad_perm:[1,0,3,2] row_mask:0xf bank_mask:0xf
	v_cvt_pk_bf16_f32 v50, v50, v92
	v_cvt_pk_bf16_f32 v34, v34, v93
	v_cvt_pk_bf16_f32 v18, v18, v94
	v_cvt_pk_bf16_f32 v2, v2, v95
	v_add_u32_e32 v82, 0x2000, v80
	s_and_saveexec_b64 s[4:5], s[2:3]
	global_store_dword v82, v50, s[66:67]
	global_store_dword v82, v34, s[66:67] offset:64
	global_store_dword v82, v18, s[66:67] offset:128
	global_store_dword v82, v2, s[66:67] offset:192
	s_or_b64 exec, exec, s[4:5]
	v_add_u32_e32 v81, 0xb000, v80
	global_load_ushort v92, v81, s[28:29]
	global_load_ushort v93, v81, s[28:29] offset:64
	global_load_ushort v94, v81, s[28:29] offset:128
	global_load_ushort v95, v81, s[28:29] offset:192
	s_waitcnt vmcnt(28)
; template <class TIn, class TOut>
; __device__ __forceinline__ void causal_swa_block(const BlockRef<TIn, TOut>& cur, const BlockRef<TIn, TOut>& nxt, int skv, int W, char* lds, Seam<TIn>& S, float TH, float TH2, int wave_s) {
;     ...
;     for (int r = 0; r < 16; ++r) { const int orow = ((r & 3) + 8 * (r >> 2)) * OSTR;
; #pragma unroll
;         for (int d0 = 0; d0 < 4; ++d0) { const float v = o[d0][r] * rli[r] * __bfloat162float(Zw[orow + d0 * 32]);
;             if constexpr (same_t<TOut, float>::v) { Ow[orow + d0 * 32] = v; }
;             else { const float vn = __shfl_xor(v, 1);
;                    if ((r32 & 1) == 0) *(unsigned*)(Ow + orow + d0 * 32) = cvtpk(v, vn); } } }
	v_mul_f32_e32 v51, v51, v79
	v_mul_f32_e32 v35, v35, v79
	v_mul_f32_e32 v19, v19, v79
	v_mul_f32_e32 v3, v3, v79
	v_lshlrev_b32_e32 v96, 16, v96
	v_lshlrev_b32_e32 v97, 16, v97
	v_lshlrev_b32_e32 v98, 16, v98
	v_lshlrev_b32_e32 v99, 16, v99
	v_mul_f32_e32 v51, v51, v96
	v_mul_f32_e32 v35, v35, v97
	v_mul_f32_e32 v19, v19, v98
	v_mul_f32_e32 v3, v3, v99
	v_mov_b32_dpp v96, v51 quad_perm:[1,0,3,2] row_mask:0xf bank_mask:0xf
	v_mov_b32_dpp v97, v35 quad_perm:[1,0,3,2] row_mask:0xf bank_mask:0xf
	v_mov_b32_dpp v98, v19 quad_perm:[1,0,3,2] row_mask:0xf bank_mask:0xf
	v_mov_b32_dpp v99, v3 quad_perm:[1,0,3,2] row_mask:0xf bank_mask:0xf
	v_cvt_pk_bf16_f32 v51, v51, v96
	v_cvt_pk_bf16_f32 v35, v35, v97
	v_cvt_pk_bf16_f32 v19, v19, v98
	v_cvt_pk_bf16_f32 v3, v3, v99
	v_add_u32_e32 v82, 0x3000, v80
	s_and_saveexec_b64 s[4:5], s[2:3]
	global_store_dword v82, v51, s[66:67]
	global_store_dword v82, v35, s[66:67] offset:64
	global_store_dword v82, v19, s[66:67] offset:128
	global_store_dword v82, v3, s[66:67] offset:192
	s_or_b64 exec, exec, s[4:5]
	v_add_u32_e32 v81, 0x10000, v80
	global_load_ushort v96, v81, s[28:29]
	global_load_ushort v97, v81, s[28:29] offset:64
	global_load_ushort v98, v81, s[28:29] offset:128
	global_load_ushort v99, v81, s[28:29] offset:192
	s_waitcnt vmcnt(32)
	v_mul_f32_e32 v52, v52, v72
	v_mul_f32_e32 v36, v36, v72
	v_mul_f32_e32 v20, v20, v72
	v_mul_f32_e32 v4, v4, v72
	v_lshlrev_b32_e32 v104, 16, v104
	v_lshlrev_b32_e32 v105, 16, v105
	v_lshlrev_b32_e32 v106, 16, v106
	v_lshlrev_b32_e32 v107, 16, v107
	v_mul_f32_e32 v52, v52, v104
	v_mul_f32_e32 v36, v36, v105
	v_mul_f32_e32 v20, v20, v106
	v_mul_f32_e32 v4, v4, v107
	v_mov_b32_dpp v104, v52 quad_perm:[1,0,3,2] row_mask:0xf bank_mask:0xf
	v_mov_b32_dpp v105, v36 quad_perm:[1,0,3,2] row_mask:0xf bank_mask:0xf
	v_mov_b32_dpp v106, v20 quad_perm:[1,0,3,2] row_mask:0xf bank_mask:0xf
	v_mov_b32_dpp v107, v4 quad_perm:[1,0,3,2] row_mask:0xf bank_mask:0xf
	v_cvt_pk_bf16_f32 v52, v52, v104
	v_cvt_pk_bf16_f32 v36, v36, v105
	v_cvt_pk_bf16_f32 v20, v20, v106
	v_cvt_pk_bf16_f32 v4, v4, v107
	v_add_u32_e32 v82, 0x8000, v80
	s_and_saveexec_b64 s[4:5], s[2:3]
	global_store_dword v82, v52, s[66:67]
	global_store_dword v82, v36, s[66:67] offset:64
	global_store_dword v82, v20, s[66:67] offset:128
	global_store_dword v82, v4, s[66:67] offset:192
	s_or_b64 exec, exec, s[4:5]
	v_add_u32_e32 v81, 0x11000, v80
	global_load_ushort v104, v81, s[28:29]
	global_load_ushort v105, v81, s[28:29] offset:64
	global_load_ushort v106, v81, s[28:29] offset:128
	global_load_ushort v107, v81, s[28:29] offset:192
	s_waitcnt vmcnt(32)
	v_mul_f32_e32 v53, v53, v73
	v_mul_f32_e32 v37, v37, v73
	v_mul_f32_e32 v21, v21, v73
	v_mul_f32_e32 v5, v5, v73
	v_lshlrev_b32_e32 v84, 16, v84
	v_lshlrev_b32_e32 v85, 16, v85
	v_lshlrev_b32_e32 v86, 16, v86
	v_lshlrev_b32_e32 v87, 16, v87
	v_mul_f32_e32 v53, v53, v84
	v_mul_f32_e32 v37, v37, v85
	v_mul_f32_e32 v21, v21, v86
	v_mul_f32_e32 v5, v5, v87
	v_mov_b32_dpp v84, v53 quad_perm:[1,0,3,2] row_mask:0xf bank_mask:0xf
	v_mov_b32_dpp v85, v37 quad_perm:[1,0,3,2] row_mask:0xf bank_mask:0xf
	v_mov_b32_dpp v86, v21 quad_perm:[1,0,3,2] row_mask:0xf bank_mask:0xf
	v_mov_b32_dpp v87, v5 quad_perm:[1,0,3,2] row_mask:0xf bank_mask:0xf
	v_cvt_pk_bf16_f32 v53, v53, v84
	v_cvt_pk_bf16_f32 v37, v37, v85
	v_cvt_pk_bf16_f32 v21, v21, v86
	v_cvt_pk_bf16_f32 v5, v5, v87
	v_add_u32_e32 v82, 0x9000, v80
	s_and_saveexec_b64 s[4:5], s[2:3]
	global_store_dword v82, v53, s[66:67]
	global_store_dword v82, v37, s[66:67] offset:64
	global_store_dword v82, v21, s[66:67] offset:128
	global_store_dword v82, v5, s[66:67] offset:192
	s_or_b64 exec, exec, s[4:5]
	v_add_u32_e32 v81, 0x12000, v80
	global_load_ushort v84, v81, s[28:29]
	global_load_ushort v85, v81, s[28:29] offset:64
	global_load_ushort v86, v81, s[28:29] offset:128
	global_load_ushort v87, v81, s[28:29] offset:192
	s_waitcnt vmcnt(32)
	v_mul_f32_e32 v54, v54, v74
	v_mul_f32_e32 v38, v38, v74
	v_mul_f32_e32 v22, v22, v74
	v_mul_f32_e32 v6, v6, v74
	v_lshlrev_b32_e32 v88, 16, v88
	v_lshlrev_b32_e32 v89, 16, v89
	v_lshlrev_b32_e32 v90, 16, v90
	v_lshlrev_b32_e32 v91, 16, v91
	v_mul_f32_e32 v54, v54, v88
	v_mul_f32_e32 v38, v38, v89
	v_mul_f32_e32 v22, v22, v90
	v_mul_f32_e32 v6, v6, v91
	v_mov_b32_dpp v88, v54 quad_perm:[1,0,3,2] row_mask:0xf bank_mask:0xf
	v_mov_b32_dpp v89, v38 quad_perm:[1,0,3,2] row_mask:0xf bank_mask:0xf
	v_mov_b32_dpp v90, v22 quad_perm:[1,0,3,2] row_mask:0xf bank_mask:0xf
	v_mov_b32_dpp v91, v6 quad_perm:[1,0,3,2] row_mask:0xf bank_mask:0xf
	v_cvt_pk_bf16_f32 v54, v54, v88
	v_cvt_pk_bf16_f32 v38, v38, v89
	v_cvt_pk_bf16_f32 v22, v22, v90
	v_cvt_pk_bf16_f32 v6, v6, v91
	v_add_u32_e32 v82, 0xa000, v80
	s_and_saveexec_b64 s[4:5], s[2:3]
	global_store_dword v82, v54, s[66:67]
	global_store_dword v82, v38, s[66:67] offset:64
	global_store_dword v82, v22, s[66:67] offset:128
	global_store_dword v82, v6, s[66:67] offset:192
	s_or_b64 exec, exec, s[4:5]
	v_add_u32_e32 v81, 0x13000, v80
	global_load_ushort v88, v81, s[28:29]
	global_load_ushort v89, v81, s[28:29] offset:64
	global_load_ushort v90, v81, s[28:29] offset:128
	global_load_ushort v91, v81, s[28:29] offset:192
	s_waitcnt vmcnt(32)
; template <class TIn, class TOut>
; __device__ __forceinline__ void causal_swa_block(const BlockRef<TIn, TOut>& cur, const BlockRef<TIn, TOut>& nxt, int skv, int W, char* lds, Seam<TIn>& S, float TH, float TH2, int wave_s) {
;     ...
;     for (int r = 0; r < 16; ++r) { const int orow = ((r & 3) + 8 * (r >> 2)) * OSTR;
; #pragma unroll
;         for (int d0 = 0; d0 < 4; ++d0) { const float v = o[d0][r] * rli[r] * __bfloat162float(Zw[orow + d0 * 32]);
;             if constexpr (same_t<TOut, float>::v) { Ow[orow + d0 * 32] = v; }
;             else { const float vn = __shfl_xor(v, 1);
;                    if ((r32 & 1) == 0) *(unsigned*)(Ow + orow + d0 * 32) = cvtpk(v, vn); } } }
	v_mul_f32_e32 v55, v55, v75
	v_mul_f32_e32 v39, v39, v75
	v_mul_f32_e32 v23, v23, v75
	v_mul_f32_e32 v7, v7, v75
	v_lshlrev_b32_e32 v92, 16, v92
	v_lshlrev_b32_e32 v93, 16, v93
	v_lshlrev_b32_e32 v94, 16, v94
	v_lshlrev_b32_e32 v95, 16, v95
	v_mul_f32_e32 v55, v55, v92
	v_mul_f32_e32 v39, v39, v93
	v_mul_f32_e32 v23, v23, v94
	v_mul_f32_e32 v7, v7, v95
	v_mov_b32_dpp v92, v55 quad_perm:[1,0,3,2] row_mask:0xf bank_mask:0xf
	v_mov_b32_dpp v93, v39 quad_perm:[1,0,3,2] row_mask:0xf bank_mask:0xf
	v_mov_b32_dpp v94, v23 quad_perm:[1,0,3,2] row_mask:0xf bank_mask:0xf
	v_mov_b32_dpp v95, v7 quad_perm:[1,0,3,2] row_mask:0xf bank_mask:0xf
	v_cvt_pk_bf16_f32 v55, v55, v92
	v_cvt_pk_bf16_f32 v39, v39, v93
	v_cvt_pk_bf16_f32 v23, v23, v94
	v_cvt_pk_bf16_f32 v7, v7, v95
	v_add_u32_e32 v82, 0xb000, v80
	s_and_saveexec_b64 s[4:5], s[2:3]
	global_store_dword v82, v55, s[66:67]
	global_store_dword v82, v39, s[66:67] offset:64
	global_store_dword v82, v23, s[66:67] offset:128
	global_store_dword v82, v7, s[66:67] offset:192
	s_or_b64 exec, exec, s[4:5]
	v_add_u32_e32 v81, 0x18000, v80
	global_load_ushort v92, v81, s[28:29]
	global_load_ushort v93, v81, s[28:29] offset:64
	global_load_ushort v94, v81, s[28:29] offset:128
	global_load_ushort v95, v81, s[28:29] offset:192
	s_waitcnt vmcnt(32)
	v_mul_f32_e32 v56, v56, v68
	v_mul_f32_e32 v40, v40, v68
	v_mul_f32_e32 v24, v24, v68
	v_mul_f32_e32 v8, v8, v68
	v_lshlrev_b32_e32 v96, 16, v96
	v_lshlrev_b32_e32 v97, 16, v97
	v_lshlrev_b32_e32 v98, 16, v98
	v_lshlrev_b32_e32 v99, 16, v99
	v_mul_f32_e32 v56, v56, v96
	v_mul_f32_e32 v40, v40, v97
	v_mul_f32_e32 v24, v24, v98
	v_mul_f32_e32 v8, v8, v99
	v_mov_b32_dpp v96, v56 quad_perm:[1,0,3,2] row_mask:0xf bank_mask:0xf
	v_mov_b32_dpp v97, v40 quad_perm:[1,0,3,2] row_mask:0xf bank_mask:0xf
	v_mov_b32_dpp v98, v24 quad_perm:[1,0,3,2] row_mask:0xf bank_mask:0xf
	v_mov_b32_dpp v99, v8 quad_perm:[1,0,3,2] row_mask:0xf bank_mask:0xf
	v_cvt_pk_bf16_f32 v56, v56, v96
	v_cvt_pk_bf16_f32 v40, v40, v97
	v_cvt_pk_bf16_f32 v24, v24, v98
	v_cvt_pk_bf16_f32 v8, v8, v99
	v_add_u32_e32 v82, 0x10000, v80
	s_and_saveexec_b64 s[4:5], s[2:3]
	global_store_dword v82, v56, s[66:67]
	global_store_dword v82, v40, s[66:67] offset:64
	global_store_dword v82, v24, s[66:67] offset:128
	global_store_dword v82, v8, s[66:67] offset:192
	s_or_b64 exec, exec, s[4:5]
	v_add_u32_e32 v81, 0x19000, v80
	global_load_ushort v96, v81, s[28:29]
	global_load_ushort v97, v81, s[28:29] offset:64
	global_load_ushort v98, v81, s[28:29] offset:128
	global_load_ushort v99, v81, s[28:29] offset:192
	s_waitcnt vmcnt(32)
	v_mul_f32_e32 v57, v57, v69
	v_mul_f32_e32 v41, v41, v69
	v_mul_f32_e32 v25, v25, v69
	v_mul_f32_e32 v9, v9, v69
	v_lshlrev_b32_e32 v104, 16, v104
	v_lshlrev_b32_e32 v105, 16, v105
	v_lshlrev_b32_e32 v106, 16, v106
	v_lshlrev_b32_e32 v107, 16, v107
	v_mul_f32_e32 v57, v57, v104
	v_mul_f32_e32 v41, v41, v105
	v_mul_f32_e32 v25, v25, v106
	v_mul_f32_e32 v9, v9, v107
	v_mov_b32_dpp v104, v57 quad_perm:[1,0,3,2] row_mask:0xf bank_mask:0xf
	v_mov_b32_dpp v105, v41 quad_perm:[1,0,3,2] row_mask:0xf bank_mask:0xf
	v_mov_b32_dpp v106, v25 quad_perm:[1,0,3,2] row_mask:0xf bank_mask:0xf
	v_mov_b32_dpp v107, v9 quad_perm:[1,0,3,2] row_mask:0xf bank_mask:0xf
	v_cvt_pk_bf16_f32 v57, v57, v104
	v_cvt_pk_bf16_f32 v41, v41, v105
	v_cvt_pk_bf16_f32 v25, v25, v106
	v_cvt_pk_bf16_f32 v9, v9, v107
	v_add_u32_e32 v82, 0x11000, v80
	s_and_saveexec_b64 s[4:5], s[2:3]
	global_store_dword v82, v57, s[66:67]
	global_store_dword v82, v41, s[66:67] offset:64
	global_store_dword v82, v25, s[66:67] offset:128
	global_store_dword v82, v9, s[66:67] offset:192
	s_or_b64 exec, exec, s[4:5]
	v_add_u32_e32 v81, 0x1a000, v80
	global_load_ushort v104, v81, s[28:29]
	global_load_ushort v105, v81, s[28:29] offset:64
	global_load_ushort v106, v81, s[28:29] offset:128
	global_load_ushort v107, v81, s[28:29] offset:192
	s_waitcnt vmcnt(32)
	v_mul_f32_e32 v58, v58, v70
	v_mul_f32_e32 v42, v42, v70
	v_mul_f32_e32 v26, v26, v70
	v_mul_f32_e32 v10, v10, v70
	v_lshlrev_b32_e32 v84, 16, v84
	v_lshlrev_b32_e32 v85, 16, v85
	v_lshlrev_b32_e32 v86, 16, v86
	v_lshlrev_b32_e32 v87, 16, v87
	v_mul_f32_e32 v58, v58, v84
	v_mul_f32_e32 v42, v42, v85
	v_mul_f32_e32 v26, v26, v86
	v_mul_f32_e32 v10, v10, v87
	v_mov_b32_dpp v84, v58 quad_perm:[1,0,3,2] row_mask:0xf bank_mask:0xf
	v_mov_b32_dpp v85, v42 quad_perm:[1,0,3,2] row_mask:0xf bank_mask:0xf
	v_mov_b32_dpp v86, v26 quad_perm:[1,0,3,2] row_mask:0xf bank_mask:0xf
	v_mov_b32_dpp v87, v10 quad_perm:[1,0,3,2] row_mask:0xf bank_mask:0xf
	v_cvt_pk_bf16_f32 v58, v58, v84
	v_cvt_pk_bf16_f32 v42, v42, v85
	v_cvt_pk_bf16_f32 v26, v26, v86
	v_cvt_pk_bf16_f32 v10, v10, v87
	v_add_u32_e32 v82, 0x12000, v80
	s_and_saveexec_b64 s[4:5], s[2:3]
	global_store_dword v82, v58, s[66:67]
	global_store_dword v82, v42, s[66:67] offset:64
	global_store_dword v82, v26, s[66:67] offset:128
	global_store_dword v82, v10, s[66:67] offset:192
	s_or_b64 exec, exec, s[4:5]
	v_add_u32_e32 v81, 0x1b000, v80
	global_load_ushort v84, v81, s[28:29]
	global_load_ushort v85, v81, s[28:29] offset:64
	global_load_ushort v86, v81, s[28:29] offset:128
	global_load_ushort v87, v81, s[28:29] offset:192
	s_waitcnt vmcnt(32)
; __device__ __forceinline__ u32x4 pack8(const f32x4 a, const f32x4 b) { u32x4 w; w.x = cvtpk_s(a[0], a[1]); w.y = cvtpk_s(a[2], a[3]); w.z = cvtpk_s(b[0], b[1]); w.w = cvtpk_s(b[2], b[3]); return w; }
; template <class TIn, class TOut>
; __device__ __forceinline__ void causal_swa_block(const BlockRef<TIn, TOut>& cur, const BlockRef<TIn, TOut>& nxt, int skv, int W, char* lds, Seam<TIn>& S, float TH, float TH2, int wave_s) {
;     ...
;     for (int r = 0; r < 16; ++r) { const int orow = ((r & 3) + 8 * (r >> 2)) * OSTR;
; #pragma unroll
;         for (int d0 = 0; d0 < 4; ++d0) { const float v = o[d0][r] * rli[r] * __bfloat162float(Zw[orow + d0 * 32]);
;             if constexpr (same_t<TOut, float>::v) { Ow[orow + d0 * 32] = v; }
;             else { const float vn = __shfl_xor(v, 1);
;                    if ((r32 & 1) == 0) *(unsigned*)(Ow + orow + d0 * 32) = cvtpk(v, vn); } } }
;     if constexpr (F32) {
; #pragma unroll
;         for (int d0 = 0; d0 < 8; ++d0) S.qr[d0] = pack8(S.tq[2 * d0], S.tq[2 * d0 + 1]); }
;     __syncthreads();
	v_mul_f32_e32 v59, v59, v71
	v_mul_f32_e32 v43, v43, v71
	v_mul_f32_e32 v27, v27, v71
	v_mul_f32_e32 v11, v11, v71
	v_lshlrev_b32_e32 v88, 16, v88
	v_lshlrev_b32_e32 v89, 16, v89
	v_lshlrev_b32_e32 v90, 16, v90
	v_lshlrev_b32_e32 v91, 16, v91
	v_mul_f32_e32 v59, v59, v88
	v_mul_f32_e32 v43, v43, v89
	v_mul_f32_e32 v27, v27, v90
	v_mul_f32_e32 v11, v11, v91
	v_mov_b32_dpp v88, v59 quad_perm:[1,0,3,2] row_mask:0xf bank_mask:0xf
	v_mov_b32_dpp v89, v43 quad_perm:[1,0,3,2] row_mask:0xf bank_mask:0xf
	v_mov_b32_dpp v90, v27 quad_perm:[1,0,3,2] row_mask:0xf bank_mask:0xf
	v_mov_b32_dpp v91, v11 quad_perm:[1,0,3,2] row_mask:0xf bank_mask:0xf
	v_cvt_pk_bf16_f32 v59, v59, v88
	v_cvt_pk_bf16_f32 v43, v43, v89
	v_cvt_pk_bf16_f32 v27, v27, v90
	v_cvt_pk_bf16_f32 v11, v11, v91
	v_add_u32_e32 v82, 0x13000, v80
	s_and_saveexec_b64 s[4:5], s[2:3]
	global_store_dword v82, v59, s[66:67]
	global_store_dword v82, v43, s[66:67] offset:64
	global_store_dword v82, v27, s[66:67] offset:128
	global_store_dword v82, v11, s[66:67] offset:192
	s_or_b64 exec, exec, s[4:5]
	s_waitcnt vmcnt(28)
	v_mul_f32_e32 v60, v60, v64
	v_mul_f32_e32 v44, v44, v64
	v_mul_f32_e32 v28, v28, v64
	v_mul_f32_e32 v12, v12, v64
	v_lshlrev_b32_e32 v92, 16, v92
	v_lshlrev_b32_e32 v93, 16, v93
	v_lshlrev_b32_e32 v94, 16, v94
	v_lshlrev_b32_e32 v95, 16, v95
	v_mul_f32_e32 v60, v60, v92
	v_mul_f32_e32 v44, v44, v93
	v_mul_f32_e32 v28, v28, v94
	v_mul_f32_e32 v12, v12, v95
	v_mov_b32_dpp v92, v60 quad_perm:[1,0,3,2] row_mask:0xf bank_mask:0xf
	v_mov_b32_dpp v93, v44 quad_perm:[1,0,3,2] row_mask:0xf bank_mask:0xf
	v_mov_b32_dpp v94, v28 quad_perm:[1,0,3,2] row_mask:0xf bank_mask:0xf
	v_mov_b32_dpp v95, v12 quad_perm:[1,0,3,2] row_mask:0xf bank_mask:0xf
	v_cvt_pk_bf16_f32 v60, v60, v92
	v_cvt_pk_bf16_f32 v44, v44, v93
	v_cvt_pk_bf16_f32 v28, v28, v94
	v_cvt_pk_bf16_f32 v12, v12, v95
	v_add_u32_e32 v82, 0x18000, v80
	s_and_saveexec_b64 s[4:5], s[2:3]
	global_store_dword v82, v60, s[66:67]
	global_store_dword v82, v44, s[66:67] offset:64
	global_store_dword v82, v28, s[66:67] offset:128
	global_store_dword v82, v12, s[66:67] offset:192
	s_or_b64 exec, exec, s[4:5]
	s_waitcnt vmcnt(24)
	v_mul_f32_e32 v61, v61, v65
	v_mul_f32_e32 v45, v45, v65
	v_mul_f32_e32 v29, v29, v65
	v_mul_f32_e32 v13, v13, v65
	v_lshlrev_b32_e32 v96, 16, v96
	v_lshlrev_b32_e32 v97, 16, v97
	v_lshlrev_b32_e32 v98, 16, v98
	v_lshlrev_b32_e32 v99, 16, v99
	v_mul_f32_e32 v61, v61, v96
	v_mul_f32_e32 v45, v45, v97
	v_mul_f32_e32 v29, v29, v98
	v_mul_f32_e32 v13, v13, v99
	v_mov_b32_dpp v96, v61 quad_perm:[1,0,3,2] row_mask:0xf bank_mask:0xf
	v_mov_b32_dpp v97, v45 quad_perm:[1,0,3,2] row_mask:0xf bank_mask:0xf
	v_mov_b32_dpp v98, v29 quad_perm:[1,0,3,2] row_mask:0xf bank_mask:0xf
	v_mov_b32_dpp v99, v13 quad_perm:[1,0,3,2] row_mask:0xf bank_mask:0xf
	v_cvt_pk_bf16_f32 v61, v61, v96
	v_cvt_pk_bf16_f32 v45, v45, v97
	v_cvt_pk_bf16_f32 v29, v29, v98
	v_cvt_pk_bf16_f32 v13, v13, v99
	v_add_u32_e32 v82, 0x19000, v80
	s_and_saveexec_b64 s[4:5], s[2:3]
	global_store_dword v82, v61, s[66:67]
	global_store_dword v82, v45, s[66:67] offset:64
	global_store_dword v82, v29, s[66:67] offset:128
	global_store_dword v82, v13, s[66:67] offset:192
	s_or_b64 exec, exec, s[4:5]
	s_waitcnt vmcnt(20)
	v_mul_f32_e32 v62, v62, v66
	v_mul_f32_e32 v46, v46, v66
	v_mul_f32_e32 v30, v30, v66
	v_mul_f32_e32 v14, v14, v66
	v_lshlrev_b32_e32 v104, 16, v104
	v_lshlrev_b32_e32 v105, 16, v105
	v_lshlrev_b32_e32 v106, 16, v106
	v_lshlrev_b32_e32 v107, 16, v107
	v_mul_f32_e32 v62, v62, v104
	v_mul_f32_e32 v46, v46, v105
	v_mul_f32_e32 v30, v30, v106
	v_mul_f32_e32 v14, v14, v107
	v_mov_b32_dpp v104, v62 quad_perm:[1,0,3,2] row_mask:0xf bank_mask:0xf
	v_mov_b32_dpp v105, v46 quad_perm:[1,0,3,2] row_mask:0xf bank_mask:0xf
	v_mov_b32_dpp v106, v30 quad_perm:[1,0,3,2] row_mask:0xf bank_mask:0xf
	v_mov_b32_dpp v107, v14 quad_perm:[1,0,3,2] row_mask:0xf bank_mask:0xf
	v_cvt_pk_bf16_f32 v62, v62, v104
	v_cvt_pk_bf16_f32 v46, v46, v105
	v_cvt_pk_bf16_f32 v30, v30, v106
	v_cvt_pk_bf16_f32 v14, v14, v107
	v_add_u32_e32 v82, 0x1a000, v80
	s_and_saveexec_b64 s[4:5], s[2:3]
	global_store_dword v82, v62, s[66:67]
	global_store_dword v82, v46, s[66:67] offset:64
	global_store_dword v82, v30, s[66:67] offset:128
	global_store_dword v82, v14, s[66:67] offset:192
	s_or_b64 exec, exec, s[4:5]
	s_waitcnt vmcnt(16)
	v_mul_f32_e32 v63, v63, v67
	v_mul_f32_e32 v47, v47, v67
	v_mul_f32_e32 v31, v31, v67
	v_mul_f32_e32 v15, v15, v67
	v_lshlrev_b32_e32 v84, 16, v84
	v_lshlrev_b32_e32 v85, 16, v85
	v_lshlrev_b32_e32 v86, 16, v86
	v_lshlrev_b32_e32 v87, 16, v87
	v_mul_f32_e32 v63, v63, v84
	v_mul_f32_e32 v47, v47, v85
	v_mul_f32_e32 v31, v31, v86
	v_mul_f32_e32 v15, v15, v87
	v_mov_b32_dpp v84, v63 quad_perm:[1,0,3,2] row_mask:0xf bank_mask:0xf
	v_mov_b32_dpp v85, v47 quad_perm:[1,0,3,2] row_mask:0xf bank_mask:0xf
	v_mov_b32_dpp v86, v31 quad_perm:[1,0,3,2] row_mask:0xf bank_mask:0xf
	v_mov_b32_dpp v87, v15 quad_perm:[1,0,3,2] row_mask:0xf bank_mask:0xf
	v_cvt_pk_bf16_f32 v63, v63, v84
	v_cvt_pk_bf16_f32 v47, v47, v85
	v_cvt_pk_bf16_f32 v31, v31, v86
	v_cvt_pk_bf16_f32 v15, v15, v87
	v_add_u32_e32 v82, 0x1b000, v80
	s_and_saveexec_b64 s[4:5], s[2:3]
	global_store_dword v82, v63, s[66:67]
	global_store_dword v82, v47, s[66:67] offset:64
	global_store_dword v82, v31, s[66:67] offset:128
	global_store_dword v82, v15, s[66:67] offset:192
	s_or_b64 exec, exec, s[4:5]
	s_and_b64 vcc, exec, s[0:1]
	s_waitcnt lgkmcnt(0)
	s_barrier
	s_cbranch_vccnz .LBB0_414
	s_mov_b64 s[84:85], s[36:37]
	s_mov_b64 s[76:77], s[40:41]
	s_mov_b64 s[70:71], s[42:43]
	s_mov_b64 s[66:67], s[44:45]
	s_mov_b64 s[28:29], s[46:47]
	s_mov_b64 s[54:55], s[90:91]
	s_mov_b32 s14, s17
	s_mov_b32 s94, s16
	s_mov_b32 s35, s78
	s_branch .LBB0_414

; #define LAS __attribute__((address_space(3)))
; #define HBAR() do { asm volatile("s_waitcnt lgkmcnt(0)" ::: "memory"); __builtin_amdgcn_s_barrier(); asm volatile("" ::: "memory"); } while (0)
; #define HG_LOADE(GV, QV, c_) do { const size_t adv_ = (size_t)(c_) * 64 * DM; _Pragma("unroll") for (int j = 0; j < 16; ++j) { GV[j] = *(const unsigned*)(gp + adv_ + (size_t)j * DM); QV[j] = *(const unsigned*)(qp + adv_ + (size_t)j * DM); } } while (0)
;     const int tid = tid_in, lane = tid & 63, w = __builtin_amdgcn_readfirstlane(tid >> 6);
;     const int bh = item >> 2, vs = item & 3, b = bh >> 4, h = bh & 15;
;     const size_t rowbase = (size_t)b * SEQ;
;     constexpr int NC = SEQ / 64;
;     if (w < 4) {
;         const int cp = lane & 15, rg = lane >> 4;
;         const bf16r* gp = G + (rowbase + 16 * rg) * DM + h * 128 + 32 * w + 2 * cp;
;         const bf16r* qp = SQ + (rowbase + 16 * rg) * DM + h * 128 + 32 * w + 2 * cp;
;         unsigned gvA[16], gvB[16]; unsigned qvA[16], qvB[16];
;     ...
;         HG_LOADE(gvA, qvA, 0); HG_LOADE(gvB, qvB, 1);
;         hgE<0>(lds, gvA, qvA, w, lane); HG_LOADE(gvA, qvA, 2);
;         HBAR();
;         for (int c = 0; c < NC; c += 2) {
;             if ((VAR & 8) == 0) hgE<1>(lds, gvB, qvB, w, lane); if ((VAR & 2) == 0) HG_LOADE(gvB, qvB, (c + 3 < NC ? c + 3 : NC - 1));
;             HBAR();
;             if ((VAR & 8) == 0) hgE<0>(lds, gvA, qvA, w, lane); if ((VAR & 2) == 0) HG_LOADE(gvA, qvA, (c + 4 < NC ? c + 4 : NC - 1));
;             HBAR();
;         }
;     ...
;     } else {
;         const int ti = w - 4, mt = tid - 256, l16 = lane & 15, kq = lane >> 4;
;         const bf16r* vp = V + (rowbase + (mt >> 2)) * DM + h * 128 + vs * 32 + (mt & 3) * 8;
;         char* ob = (char*)(O + (rowbase + 16 * ti) * DM + h * 128 + vs * 32);
;         const unsigned ol = (4 * kq * DM + l16) * 2;
;         for (int i = mt; i < ST_BYTES / 4; i += 256) ((LAS unsigned*)(lds + OFF_ST))[i] = 0u;
.LBB0_1174:
	s_ashr_i32 s14, s64, 6
	v_readfirstlane_b32 s0, v85
	s_ashr_i32 s15, s14, 31
	s_ashr_i32 s97, s0, 6
	s_bfe_u32 s2, s64, 0x40002
	s_lshl_b64 s[60:61], s[14:15], 13
	s_cmp_gt_i32 s97, 3
	s_mov_b64 s[16:17], -1
	s_cbranch_scc0 .LBB0_1181
	s_and_saveexec_b64 s[16:17], s[4:5]
	s_cbranch_execz .LBB0_1178
	s_mov_b64 s[20:21], 0
	s_waitcnt vmcnt(0)
	v_mov_b32_e32 v0, v134
	v_mov_b32_e32 v1, v133

; #define LAS __attribute__((address_space(3)))
; #define HBAR() do { asm volatile("s_waitcnt lgkmcnt(0)" ::: "memory"); __builtin_amdgcn_s_barrier(); asm volatile("" ::: "memory"); } while (0)
;     ...
;     const int tq = 16 * ti + l16 - 4 * kq;
; #pragma unroll
;     for (int si = 0; si < 4; ++si)
; #pragma unroll
;         for (int j = 0; j < 4; ++j) if (16 * si + j > tq) as[si][j] = 0.f;
;     ...
;         const int ti = w - 4, mt = tid - 256, l16 = lane & 15, kq = lane >> 4;
;         const bf16r* vp = V + (rowbase + (mt >> 2)) * DM + h * 128 + vs * 32 + (mt & 3) * 8;
;         char* ob = (char*)(O + (rowbase + 16 * ti) * DM + h * 128 + vs * 32);
;         const unsigned ol = (4 * kq * DM + l16) * 2;
;         for (int i = mt; i < ST_BYTES / 4; i += 256) ((LAS unsigned*)(lds + OFF_ST))[i] = 0u;
;         f32x4 st[2][2];
; #pragma unroll
;         for (int ds = 0; ds < 2; ++ds) { st[ds][0] = (f32x4){0.f, 0.f, 0.f, 0.f}; st[ds][1] = st[ds][0]; }
;         u32x4 vA = *(const u32x4*)vp, vB = *(const u32x4*)(vp + (size_t)64 * DM);
;         hgV<0>(lds, vA, mt); vA = *(const u32x4*)(vp + (size_t)2 * 64 * DM);
;         HBAR();
;         for (int c = 0; c < NC; c += 2) {
.LBB0_1178:
	s_or_b64 exec, exec, s[16:17]
	s_waitcnt vmcnt(0)
	v_lshl_add_u64 v[0:1], s[60:61], 0, v[80:81]
	v_lshlrev_b64 v[0:1], 12, v[0:1]
	v_lshl_add_u64 v[0:1], s[72:73], 0, v[0:1]
	s_lshl_b32 s48, s2, 8
	s_lshl_b32 s65, s64, 6
	v_lshl_add_u64 v[0:1], v[0:1], 0, s[48:49]
	s_and_b32 s48, s65, 0xc0
	v_lshl_add_u64 v[0:1], v[0:1], 0, s[48:49]
	v_mov_b32_e32 v89, v83
	v_lshl_add_u64 v[90:91], v[0:1], 0, v[88:89]
	global_load_dwordx4 v[10:13], v[90:91], off
	v_add_co_u32_e32 v0, vcc, 0x40000, v90
	s_lshl_b64 s[0:1], s[14:15], 25
	s_nop 0
	v_addc_co_u32_e32 v1, vcc, 0, v91, vcc
	s_mov_b32 s15, 0x80000
	s_waitcnt vmcnt(1)
	v_add_co_u32_e32 v4, vcc, s15, v90
	global_load_dwordx4 v[0:3], v[0:1], off
	s_nop 0
	v_addc_co_u32_e32 v5, vcc, 0, v91, vcc
	global_load_dwordx4 v[4:7], v[4:5], off
	s_add_i32 s16, s97, -4
	s_lshl_b32 s14, s16, 5
	v_or_b32_e32 v9, s14, v114
	v_or_b32_e32 v14, s14, v120
	v_mul_lo_u32 v89, v9, s19
	v_lshlrev_b32_e32 v9, 2, v14
	s_lshl_b32 s48, s16, 4
	v_add_u32_e32 v95, 0, v9
	v_or_b32_e32 v9, s48, v114
	s_movk_i32 s14, 0x110
	v_lshlrev_b32_e32 v94, 1, v14
	s_lshl_b64 s[76:77], s[48:49], 12
	v_mul_lo_u32 v14, v9, s14
	v_sub_u32_e32 v9, v9, v120
	s_add_u32 s0, s0, s76
	v_cmp_gt_i32_e64 s[46:47], 50, v9
	v_cmp_gt_i32_e64 s[14:15], 51, v9
	v_cmp_gt_i32_e64 s[44:45], 49, v9
	s_addc_u32 s1, s1, s77
	s_and_b64 s[46:47], s[14:15], s[46:47]
	v_cmp_gt_i32_e64 s[42:43], 48, v9
	s_and_b64 s[44:45], s[46:47], s[44:45]
	v_cmp_gt_i32_e64 s[40:41], 35, v9
	s_and_b64 s[42:43], s[44:45], s[42:43]
	v_cmp_gt_i32_e64 s[38:39], 34, v9
	s_and_b64 s[40:41], s[42:43], s[40:41]
	v_cmp_gt_i32_e64 s[36:37], 33, v9
	s_and_b64 s[38:39], s[40:41], s[38:39]
	v_cmp_gt_i32_e64 s[34:35], 32, v9
	s_and_b64 s[36:37], s[38:39], s[36:37]
	v_cmp_gt_i32_e64 s[30:31], 19, v9
	s_and_b64 s[34:35], s[36:37], s[34:35]
	v_cmp_gt_i32_e64 s[28:29], 18, v9
	s_and_b64 s[30:31], s[34:35], s[30:31]
	v_cmp_gt_i32_e64 s[26:27], 17, v9
	s_and_b64 s[28:29], s[30:31], s[28:29]
	v_cmp_gt_i32_e64 s[24:25], 16, v9
	s_and_b64 s[26:27], s[28:29], s[26:27]
	v_cmp_gt_i32_e64 s[22:23], 3, v9
	s_and_b64 s[24:25], s[26:27], s[24:25]
	v_cmp_gt_i32_e64 s[20:21], 2, v9
	s_and_b32 s48, s65, 0xf00
	s_and_b32 s64, s64, 3
	s_and_b64 s[22:23], s[24:25], s[22:23]
	v_cmp_gt_i32_e64 s[16:17], 1, v9
	s_or_b32 s0, s0, s48
	s_lshl_b32 s48, s64, 6
	s_and_b64 s[20:21], s[22:23], s[20:21]
	v_mov_b32_e32 v8, 0
	v_cmp_gt_i32_e32 vcc, 0, v9
	s_or_b32 s0, s0, s48
	s_and_b64 s[16:17], s[20:21], s[16:17]
	s_mov_b32 s3, -2
	v_add_u32_e32 v96, v130, v94
	v_add_u32_e32 v97, v131, v89
	v_add_u32_e32 v98, v132, v94
	v_add_u32_e32 v99, v115, v14
	v_lshl_add_u64 v[92:93], v[86:87], 0, s[0:1]
	v_mbcnt_lo_u32_b32 v248, -1, 0
	v_mbcnt_hi_u32_b32 v248, -1, v248
	v_and_b32_e32 v249, 15, v248
	v_lshrrev_b32_e32 v248, 4, v248
	v_mul_u32_u24_e32 v249, 0xffe, v249
	v_mul_u32_u24_e32 v248, 0x3ff8, v248
	v_sub_u32_e32 v248, v249, v248
	v_ashrrev_i32_e32 v249, 31, v248
	v_lshl_add_u64 v[244:245], v[92:93], 0, v[248:249]
	v_mov_b32_e32 v248, 0x40000
	v_mov_b32_e32 v249, 0
	v_lshl_add_u64 v[246:247], v[244:245], 0, v[248:249]
	s_and_b64 s[64:65], s[16:17], vcc
	v_mov_b32_e32 v9, v8
	v_mov_b32_e32 v20, v8
	v_mov_b32_e32 v21, v8
	v_mov_b32_e32 v22, v8
	s_waitcnt vmcnt(2)
	ds_write_b16 v135, v10 offset:53248
	ds_write_b16_d16_hi v135, v10 offset:53392
	ds_write_b16 v135, v11 offset:53536
	ds_write_b16_d16_hi v135, v11 offset:53680
	ds_write_b16 v135, v12 offset:53824
	ds_write_b16_d16_hi v135, v12 offset:53968
	ds_write_b16 v135, v13 offset:54112
	ds_write_b16_d16_hi v135, v13 offset:54256
	s_waitcnt lgkmcnt(0)
	s_barrier
	v_mov_b32_e32 v10, v8
	v_mov_b32_e32 v11, v8
	v_mov_b32_e32 v23, v8
	v_mov_b32_e32 v16, v8
	v_mov_b32_e32 v17, v8
	v_mov_b32_e32 v18, v8
	v_mov_b32_e32 v19, v8
	v_mov_b32_e32 v12, v8
	v_mov_b32_e32 v13, v8
	v_mov_b32_e32 v14, v8
	v_mov_b32_e32 v15, v8
	s_waitcnt vmcnt(1)
.LBB0_1179:
	v_add_u32_e32 v28, v117, v84
	ds_read_b128 v[100:103], v99
	ds_read_b128 v[104:107], v99 offset:64
	ds_read_b128 v[108:111], v28
	ds_read_b128 v[138:141], v28 offset:64
	ds_read_b128 v[142:145], v28 offset:4352
	ds_read_b128 v[146:149], v28 offset:4416
	ds_read_b128 v[48:51], v99 offset:128
	ds_read_b128 v[24:27], v99 offset:192
	ds_read_b128 v[56:59], v28 offset:128
	ds_read_b128 v[32:35], v28 offset:192
	ds_read_b128 v[150:153], v28 offset:4480
	ds_read_b128 v[52:55], v28 offset:4544
	v_add_u32_e32 v28, v116, v84
	ds_read_b128 v[154:157], v28 offset:17408
	ds_read_b128 v[158:161], v28 offset:17472
	ds_read_b128 v[162:165], v28 offset:17536
	ds_read_b128 v[60:63], v28 offset:17600
	ds_read_b128 v[166:169], v28 offset:21760
	ds_read_b128 v[170:173], v28 offset:21824
	ds_read_b128 v[174:177], v28 offset:21888
	ds_read_b128 v[64:67], v28 offset:21952
	ds_read_b128 v[178:181], v28 offset:26112
	ds_read_b128 v[182:185], v28 offset:26176
	ds_read_b128 v[186:189], v28 offset:26240
	ds_read_b128 v[68:71], v28 offset:26304
	ds_read_b128 v[190:193], v28 offset:30464
	ds_read_b128 v[194:197], v28 offset:30528
	ds_read_b128 v[76:79], v28 offset:30592
	ds_read_b128 v[72:75], v28 offset:30656
	v_add_u32_e32 v36, v118, v119
	v_add_u32_e32 v28, 0xd000, v36
	v_add_u32_e32 v36, 0xd800, v36
	v_add_u32_e32 v112, v118, v84
	ds_read2_b64 v[40:43], v28 offset1:4
	ds_read2_b64 v[28:31], v28 offset0:8 offset1:12
	ds_read2_b64 v[44:47], v36 offset0:32 offset1:36
	ds_read2_b64 v[36:39], v36 offset0:40 offset1:44
	v_add_u32_e32 v113, v115, v89
	ds_read_b128 v[202:205], v112 offset:53248
	ds_read_b128 v[208:211], v112 offset:53312
	ds_read_b128 v[212:215], v112 offset:55552
	ds_read_b128 v[216:219], v112 offset:55616
	ds_read_b128 v[220:223], v113 offset:34816
	ds_read_b128 v[224:227], v113 offset:34880
	ds_read_b128 v[228:231], v113 offset:37120
	ds_read_b128 v[232:235], v113 offset:37184
	ds_read_b128 v[236:239], v95 offset:57856
	ds_read_b128 v[240:243], v95 offset:57920
	s_add_i32 s3, s3, 2
	s_waitcnt lgkmcnt(14)
; __device__ __forceinline__ unsigned cvtpk_s(float lo, float hi) { f32x2_t v = {lo, hi}; bf16x2_t b = __builtin_convertvector(v, bf16x2_t); return __builtin_bit_cast(unsigned, b); }
; #define MFMA16(a, b, c) __builtin_amdgcn_mfma_f32_16x16x32_bf16((a), (b), (c), 0, 0, 0)
;     ...
;     for (int kk = 0; kk < 4; ++kk) { o[0] = MFMA16(qf[kk], sb[0][kk], o[0]); o[1] = MFMA16(qf[kk], sb[1][kk], o[1]);
; #pragma unroll
;         for (int si = 0; si < 4; ++si) as[si] = MFMA16(kf[si][kk], qf[kk], as[si]); }
; #pragma unroll
;     for (int ds = 0; ds < 2; ++ds)
; #pragma unroll
;         for (int vh = 0; vh < 2; ++vh) { st[ds][vh] = st[ds][vh] * dl[ds];
; #pragma unroll
;             for (int kk = 0; kk < 2; ++kk) st[ds][vh] = MFMA16(kt[ds][kk], vv[vh][kk], st[ds][vh]); }
;     const int tq = 16 * ti + l16 - 4 * kq;
; #pragma unroll
;     for (int si = 0; si < 4; ++si)
; #pragma unroll
;         for (int j = 0; j < 4; ++j) if (16 * si + j > tq) as[si][j] = 0.f;
; #pragma unroll
;     for (int p = 0; p < 2; ++p) {
;         u32x4 pw; pw.x = cvtpk_s(as[2 * p][0], as[2 * p][1]); pw.y = cvtpk_s(as[2 * p][2], as[2 * p][3]); pw.z = cvtpk_s(as[2 * p + 1][0], as[2 * p + 1][1]); pw.w = cvtpk_s(as[2 * p + 1][2], as[2 * p + 1][3]);
; #pragma unroll
;         for (int vh = 0; vh < 2; ++vh) { const u32x4 vw = {va[vh][p].x, va[vh][p].y, vb2[vh][p].x, vb2[vh][p].y};
;             o[vh] = MFMA16(__builtin_bit_cast(bf16x8, pw), __builtin_bit_cast(bf16x8, vw), o[vh]); }
;     }
;     if ((VAR & 1) == 0 || o[0][0] == 12345.678f) {
; #pragma unroll
;     for (int vh = 0; vh < 2; ++vh)
; #pragma unroll
;         for (int j = 0; j < 4; ++j) *(bf16r*)(ob + (size_t)j * DM * 2 + vh * 32 + ol) = (bf16r)(cvtpk_s(o[vh][j], 0.f) & 0xffffu);
;     }
;     ...
;             hgV<1>(lds, vB, mt); vB = *(const u32x4*)(vp + (size_t)(c + 3 < NC ? c + 3 : NC - 1) * 64 * DM);
	v_mfma_f32_16x16x32_bf16 v[142:145], v[142:145], v[100:103], 0
	s_waitcnt lgkmcnt(1)
	v_pk_mul_f32 v[20:21], v[20:21], v[236:237]
	v_pk_mul_f32 v[22:23], v[22:23], v[238:239]
	v_pk_mul_f32 v[8:9], v[8:9], v[236:237]
	v_mfma_f32_16x16x32_bf16 v[154:157], v[154:157], v[100:103], 0
	v_mul_f32_e64 v10, v10, v238
	v_mul_f32_e64 v11, v11, v239
	s_waitcnt lgkmcnt(0)
	v_pk_mul_f32 v[16:17], v[16:17], v[240:241]
	v_pk_mul_f32 v[18:19], v[18:19], v[242:243]
	v_mfma_f32_16x16x32_bf16 v[166:169], v[166:169], v[100:103], 0
	v_mul_f32_e64 v12, v12, v240
	v_mul_f32_e64 v13, v13, v241
	v_pk_mul_f32 v[14:15], v[14:15], v[242:243]
	s_movk_i32 s0, 0x1000
	v_mfma_f32_16x16x32_bf16 v[178:181], v[178:181], v[100:103], 0
	v_add_co_u32_e32 v112, vcc, s0, v92
	s_movk_i32 s0, 0x3000
	v_mfma_f32_16x16x32_bf16 v[190:193], v[190:193], v[100:103], 0
	v_addc_co_u32_e32 v113, vcc, 0, v93, vcc
	v_mfma_f32_16x16x32_bf16 v[100:103], v[108:111], v[100:103], 0
	v_mfma_f32_16x16x32_bf16 v[108:111], v[220:223], v[212:215], v[20:23]
	v_mfma_f32_16x16x32_bf16 v[142:145], v[146:149], v[104:107], v[142:145]
	v_mfma_f32_16x16x32_bf16 v[146:149], v[158:161], v[104:107], v[154:157]
	v_mfma_f32_16x16x32_bf16 v[154:157], v[170:173], v[104:107], v[166:169]
	v_mfma_f32_16x16x32_bf16 v[8:11], v[220:223], v[202:205], v[8:11]
	v_mfma_f32_16x16x32_bf16 v[202:205], v[228:231], v[202:205], v[16:19]
	v_mfma_f32_16x16x32_bf16 v[158:161], v[182:185], v[104:107], v[178:181]
	v_mfma_f32_16x16x32_bf16 v[166:169], v[194:197], v[104:107], v[190:193]
	v_mfma_f32_16x16x32_bf16 v[100:103], v[138:141], v[104:107], v[100:103]
	v_mfma_f32_16x16x32_bf16 v[16:19], v[224:227], v[216:219], v[108:111]
	v_mfma_f32_16x16x32_bf16 v[108:111], v[162:165], v[48:51], v[146:149]
	v_mfma_f32_16x16x32_bf16 v[138:141], v[174:177], v[48:51], v[154:157]
	s_nop 1
	v_add_co_u32_e32 v146, vcc, s67, v92
	v_mfma_f32_16x16x32_bf16 v[212:215], v[228:231], v[212:215], v[12:15]
	s_nop 0
	v_addc_co_u32_e32 v147, vcc, 0, v93, vcc
	v_add_co_u32_e32 v148, vcc, s0, v92
	v_mfma_f32_16x16x32_bf16 v[104:107], v[150:153], v[48:51], v[142:145]
	v_add_u32_e32 v152, v121, v94
	s_min_u32 s0, s3, 0x7c
	s_lshl_b32 s48, s0, 18
	v_mfma_f32_16x16x32_bf16 v[142:145], v[186:189], v[48:51], v[158:161]
	v_addc_co_u32_e32 v149, vcc, 0, v93, vcc
	v_lshl_add_u64 v[150:151], v[90:91], 0, s[48:49]
	v_mfma_f32_16x16x32_bf16 v[76:79], v[76:79], v[48:51], v[166:169]
	s_mov_b32 s0, 0xc0000
	v_add_co_u32_e32 v150, vcc, s0, v150
	v_mfma_f32_16x16x32_bf16 v[48:51], v[56:59], v[48:51], v[100:103]
	s_nop 0
	v_addc_co_u32_e32 v151, vcc, 0, v151, vcc
	v_mfma_f32_16x16x32_bf16 v[56:59], v[60:63], v[24:27], v[108:111]
	v_cvt_pk_bf16_f32 v102, v16, v17
	v_cvt_pk_bf16_f32 v103, v18, v19
	v_mfma_f32_16x16x32_bf16 v[60:63], v[64:67], v[24:27], v[138:141]
	v_mfma_f32_16x16x32_bf16 v[20:23], v[224:227], v[208:211], v[8:11]
	s_nop 3
	v_cndmask_b32_e64 v58, v58, 0, s[20:21]
	s_nop 1
	v_cndmask_b32_e64 v62, v62, 0, s[28:29]
	v_cndmask_b32_e64 v60, v60, 0, s[24:25]
	v_mfma_f32_16x16x32_bf16 v[8:11], v[232:235], v[216:219], v[212:215]
	v_cndmask_b32_e64 v56, v56, 0, s[64:65]
	v_cvt_pk_bf16_f32 v100, v20, v21
	v_cvt_pk_bf16_f32 v101, v22, v23
	v_mfma_f32_16x16x32_bf16 v[52:55], v[52:55], v[24:27], v[104:107]
	v_mfma_f32_16x16x32_bf16 v[64:67], v[68:71], v[24:27], v[142:145]
	s_nop 2
	v_cvt_pk_bf16_f32 v106, v8, v9
	v_cvt_pk_bf16_f32 v107, v10, v11
	v_mfma_f32_16x16x32_bf16 v[68:71], v[72:75], v[24:27], v[76:79]
	v_mfma_f32_16x16x32_bf16 v[24:27], v[32:35], v[24:27], v[48:51]
	v_cndmask_b32_e64 v35, v63, 0, s[30:31]
	v_cndmask_b32_e64 v34, v61, 0, s[26:27]
	v_cndmask_b32_e64 v33, v59, 0, s[22:23]
	v_cndmask_b32_e64 v32, v57, 0, s[16:17]
	v_mfma_f32_16x16x32_bf16 v[12:15], v[232:235], v[208:211], v[202:205]
	v_cvt_pk_bf16_f32 v32, v56, v32
	v_cvt_pk_bf16_f32 v33, v58, v33
	v_cvt_pk_bf16_f32 v34, v60, v34
	v_cvt_pk_bf16_f32 v35, v62, v35
	v_cndmask_b32_e64 v48, v69, 0, s[44:45]
	s_nop 2
	v_cvt_pk_bf16_f32 v104, v12, v13
	v_cvt_pk_bf16_f32 v105, v14, v15
	ds_write_b64 v152, v[100:101]
	ds_write_b64 v152, v[102:103] offset:4352
	ds_write_b64 v96, v[104:105]
	ds_write_b64 v96, v[106:107] offset:4352
	s_waitcnt vmcnt(3)
	ds_write_b16 v136, v0
	ds_write_b16_d16_hi v136, v0 offset:144
	ds_write_b16 v136, v1 offset:288
	ds_write_b16_d16_hi v136, v1 offset:432
	ds_write_b16 v136, v2 offset:576
	v_cndmask_b32_e64 v0, v71, 0, s[14:15]
	v_cndmask_b32_e64 v1, v70, 0, s[46:47]
	v_cndmask_b32_e64 v49, v68, 0, s[42:43]
	v_cndmask_b32_e64 v50, v67, 0, s[40:41]
	v_cndmask_b32_e64 v51, v66, 0, s[38:39]
	v_cndmask_b32_e64 v65, v65, 0, s[36:37]
	v_cndmask_b32_e64 v64, v64, 0, s[34:35]
	v_mfma_f32_16x16x32_bf16 v[24:27], v[40:43], v[32:35], v[24:27]
	v_cvt_pk_bf16_f32 v40, v64, v65
	v_cvt_pk_bf16_f32 v41, v51, v50
	v_cvt_pk_bf16_f32 v42, v49, v48
	v_cvt_pk_bf16_f32 v43, v1, v0
	v_mfma_f32_16x16x32_bf16 v[32:35], v[44:47], v[32:35], v[52:55]
	ds_write_b16_d16_hi v136, v2 offset:720
	ds_write_b16 v136, v3 offset:864
	ds_write_b16_d16_hi v136, v3 offset:1008
	v_mfma_f32_16x16x32_bf16 v[24:27], v[28:31], v[40:43], v[24:27]
	v_mfma_f32_16x16x32_bf16 v[0:3], v[36:39], v[40:43], v[32:35]
	s_nop 6
	v_cvt_pk_bf16_f32 v24, v24, v25
	v_cvt_pk_bf16_f32 v25, v26, v27
	v_cvt_pk_bf16_f32 v26, v0, v1
	v_cvt_pk_bf16_f32 v27, v2, v3
	global_store_dwordx2 v[244:245], v[24:25], off
	global_store_dwordx2 v[244:245], v[26:27], off offset:32
	global_load_dwordx4 v[0:3], v[150:151], off
	v_add_u32_e32 v25, v122, v119
	v_add_u32_e32 v24, v121, v84
	v_add_u32_e32 v26, 0x800, v25
	s_waitcnt lgkmcnt(0)
	s_barrier
; #define LAS __attribute__((address_space(3)))
;     ...
;     const LAS unsigned char* qrow = base + OFF_Q + (16 * ti + l16) * QS + kq * 16;
;     const LAS unsigned char* krow = base + OFF_K + l16 * QS + kq * 16;
;     const LAS unsigned char* srow = lds + OFF_ST + SET * ST_BYTES + l16 * QS + kq * 16;
;     const LAS unsigned char* vrow = base + OFF_VT + l16 * TS;
; #pragma unroll
;     for (int kk = 0; kk < 4; ++kk) { qf[kk] = *(const LAS bf16x8*)(qrow + kk * 64); sb[0][kk] = *(const LAS bf16x8*)(srow + kk * 64); sb[1][kk] = *(const LAS bf16x8*)(srow + 16 * QS + kk * 64); }
; #pragma unroll
;     for (int si = 0; si < 4; ++si)
; #pragma unroll
;         for (int kk = 0; kk < 4; ++kk) kf[si][kk] = *(const LAS bf16x8*)(krow + si * 16 * QS + kk * 64);
; #pragma unroll
;     for (int vh = 0; vh < 2; ++vh)
; #pragma unroll
;         for (int p = 0; p < 2; ++p) { va[vh][p] = *(const LAS u32x2*)(vrow + vh * 16 * TS + kq * 8 + p * 64); vb2[vh][p] = *(const LAS u32x2*)(vrow + vh * 16 * TS + kq * 8 + p * 64 + 32); }
; #pragma unroll
;     for (int kk = 0; kk < 2; ++kk) { vv[0][kk] = *(const LAS bf16x8*)(vrow + kk * 64 + kq * 16); vv[1][kk] = *(const LAS bf16x8*)(vrow + 16 * TS + kk * 64 + kq * 16);
;         kt[0][kk] = *(const LAS bf16x8*)(base + OFF_KT + (32 * ti + l16) * TS + kk * 64 + kq * 16); kt[1][kk] = *(const LAS bf16x8*)(base + OFF_KT + (32 * ti + 16 + l16) * TS + kk * 64 + kq * 16); }
;     dl[0] = *(const LAS f32x4*)(base + OFF_DL + (32 * ti + 4 * kq) * 4); dl[1] = *(const LAS f32x4*)(base + OFF_DL + (32 * ti + 16 + 4 * kq) * 4);
;     __builtin_amdgcn_sched_barrier(0);
;     f32x4 o[2], as[4];
;     o[0] = (f32x4){0.f, 0.f, 0.f, 0.f}; o[1] = o[0];
; #pragma unroll
;     for (int si = 0; si < 4; ++si) as[si] = (f32x4){0.f, 0.f, 0.f, 0.f};
; #pragma unroll
;     for (int kk = 0; kk < 4; ++kk) { o[0] = MFMA16(qf[kk], sb[0][kk], o[0]); o[1] = MFMA16(qf[kk], sb[1][kk], o[1]);
; #pragma unroll
;         for (int si = 0; si < 4; ++si) as[si] = MFMA16(kf[si][kk], qf[kk], as[si]); }
; #pragma unroll
;     for (int ds = 0; ds < 2; ++ds)
; #pragma unroll
;         for (int vh = 0; vh < 2; ++vh) { st[ds][vh] = st[ds][vh] * dl[ds];
; #pragma unroll
;             for (int kk = 0; kk < 2; ++kk) st[ds][vh] = MFMA16(kt[ds][kk], vv[vh][kk], st[ds][vh]); }
;     const int tq = 16 * ti + l16 - 4 * kq;
; #pragma unroll
;     for (int si = 0; si < 4; ++si)
; #pragma unroll
	s_sleep 10
	v_add_u32_e32 v112, v122, v84
	v_add_u32_e32 v113, 0x1c600, v95
	ds_read_b128 v[100:103], v99 offset:58368
	ds_read_b128 v[104:107], v99 offset:58432
	ds_read_b128 v[108:111], v24
	ds_read_b128 v[138:141], v24 offset:64
	ds_read_b128 v[142:145], v24 offset:4352
	ds_read_b128 v[146:149], v24 offset:4416
	ds_read_b128 v[68:71], v99 offset:58496
	ds_read_b128 v[36:39], v99 offset:58560
	ds_read_b128 v[72:75], v24 offset:128
	ds_read_b128 v[44:47], v24 offset:192
	ds_read_b128 v[150:153], v24 offset:4480
	ds_read_b128 v[48:51], v24 offset:4544
	ds_read_b128 v[154:157], v137
	ds_read_b128 v[158:161], v137 offset:64
	ds_read_b128 v[162:165], v137 offset:128
	ds_read_b128 v[52:55], v137 offset:192
	ds_read_b128 v[166:169], v137 offset:4352
	ds_read_b128 v[170:173], v137 offset:4416
	ds_read_b128 v[174:177], v137 offset:4480
	ds_read_b128 v[56:59], v137 offset:4544
	ds_read_b128 v[178:181], v137 offset:8704
	ds_read_b128 v[182:185], v137 offset:8768
	ds_read_b128 v[186:189], v137 offset:8832
	ds_read_b128 v[60:63], v137 offset:8896
	ds_read_b128 v[190:193], v137 offset:13056
	ds_read_b128 v[194:197], v137 offset:13120
	ds_read_b128 v[76:79], v137 offset:13184
	ds_read_b128 v[64:67], v137 offset:13248
	ds_read2_b64 v[40:43], v25 offset1:4
	ds_read2_b64 v[28:31], v25 offset0:8 offset1:12
	ds_read2_b64 v[32:35], v26 offset0:32 offset1:36
	ds_read2_b64 v[24:27], v26 offset0:40 offset1:44
	ds_read_b128 v[202:205], v112
	ds_read_b128 v[208:211], v112 offset:64
	ds_read_b128 v[212:215], v112 offset:2304
	ds_read_b128 v[216:219], v112 offset:2368
	ds_read_b128 v[220:223], v97
	ds_read_b128 v[224:227], v97 offset:64
	ds_read_b128 v[228:231], v97 offset:2304
	ds_read_b128 v[232:235], v97 offset:2368
	ds_read_b128 v[236:239], v113
	ds_read_b128 v[240:243], v113 offset:64
	s_waitcnt lgkmcnt(14)
	v_mfma_f32_16x16x32_bf16 v[142:145], v[142:145], v[100:103], 0
	s_waitcnt lgkmcnt(1)
	v_pk_mul_f32 v[22:23], v[22:23], v[238:239]
	v_pk_mul_f32 v[20:21], v[20:21], v[236:237]
	v_pk_mul_f32 v[18:19], v[18:19], v[238:239]
	v_mfma_f32_16x16x32_bf16 v[154:157], v[154:157], v[100:103], 0
	v_mul_f32_e64 v16, v16, v236
	v_mul_f32_e64 v17, v17, v237
	s_waitcnt lgkmcnt(0)
	v_pk_mul_f32 v[14:15], v[14:15], v[242:243]
	v_pk_mul_f32 v[12:13], v[12:13], v[240:241]
	v_mfma_f32_16x16x32_bf16 v[166:169], v[166:169], v[100:103], 0
	v_mul_f32_e64 v10, v10, v242
	v_mul_f32_e64 v11, v11, v243
	v_pk_mul_f32 v[8:9], v[8:9], v[240:241]
	s_mov_b32 s0, 0x40000
	v_mfma_f32_16x16x32_bf16 v[178:181], v[178:181], v[100:103], 0
	v_add_co_u32_e32 v112, vcc, s0, v92
	s_mov_b32 s0, 0x42000
	v_mfma_f32_16x16x32_bf16 v[190:193], v[190:193], v[100:103], 0
	v_addc_co_u32_e32 v113, vcc, 0, v93, vcc
	v_mfma_f32_16x16x32_bf16 v[100:103], v[108:111], v[100:103], 0
	v_mfma_f32_16x16x32_bf16 v[20:23], v[220:223], v[202:205], v[20:23]
	v_mfma_f32_16x16x32_bf16 v[16:19], v[220:223], v[212:215], v[16:19]
	v_mfma_f32_16x16x32_bf16 v[12:15], v[228:231], v[202:205], v[12:15]
	v_mfma_f32_16x16x32_bf16 v[108:111], v[228:231], v[212:215], v[8:11]
	v_mfma_f32_16x16x32_bf16 v[142:145], v[146:149], v[104:107], v[142:145]
	v_mfma_f32_16x16x32_bf16 v[146:149], v[158:161], v[104:107], v[154:157]
	v_mfma_f32_16x16x32_bf16 v[154:157], v[170:173], v[104:107], v[166:169]
	v_mfma_f32_16x16x32_bf16 v[158:161], v[182:185], v[104:107], v[178:181]
	v_mfma_f32_16x16x32_bf16 v[166:169], v[194:197], v[104:107], v[190:193]
	v_mfma_f32_16x16x32_bf16 v[100:103], v[138:141], v[104:107], v[100:103]
	v_mfma_f32_16x16x32_bf16 v[8:11], v[224:227], v[208:211], v[20:23]
	v_mfma_f32_16x16x32_bf16 v[20:23], v[224:227], v[216:219], v[16:19]
	v_mfma_f32_16x16x32_bf16 v[16:19], v[232:235], v[208:211], v[12:15]
	v_mfma_f32_16x16x32_bf16 v[12:15], v[232:235], v[216:219], v[108:111]
	v_mfma_f32_16x16x32_bf16 v[108:111], v[162:165], v[68:71], v[146:149]
	v_mfma_f32_16x16x32_bf16 v[138:141], v[174:177], v[68:71], v[154:157]
	v_mfma_f32_16x16x32_bf16 v[104:107], v[150:153], v[68:71], v[142:145]
	s_nop 1
	v_add_u32_e32 v154, v117, v94
	v_add_co_u32_e32 v150, vcc, s70, v92
	v_mfma_f32_16x16x32_bf16 v[142:145], v[186:189], v[68:71], v[158:161]
	s_nop 0
	v_addc_co_u32_e32 v151, vcc, 0, v93, vcc
	v_add_co_u32_e32 v146, vcc, s0, v92
	v_mfma_f32_16x16x32_bf16 v[76:79], v[76:79], v[68:71], v[166:169]
	s_nop 0
	v_addc_co_u32_e32 v147, vcc, 0, v93, vcc
	s_min_u32 s0, s3, 0x7b
	v_mfma_f32_16x16x32_bf16 v[68:71], v[72:75], v[68:71], v[100:103]
	v_cvt_pk_bf16_f32 v72, v8, v9
	v_cvt_pk_bf16_f32 v73, v10, v11
	v_cvt_pk_bf16_f32 v74, v20, v21
	v_mfma_f32_16x16x32_bf16 v[52:55], v[52:55], v[36:39], v[108:111]
	v_cvt_pk_bf16_f32 v102, v12, v13
	v_cvt_pk_bf16_f32 v103, v14, v15
	v_cvt_pk_bf16_f32 v75, v22, v23
	v_mfma_f32_16x16x32_bf16 v[56:59], v[56:59], v[36:39], v[138:141]
	v_cvt_pk_bf16_f32 v100, v16, v17
	s_nop 2
	v_cndmask_b32_e64 v54, v54, 0, s[20:21]
	v_cndmask_b32_e64 v52, v52, 0, s[64:65]
	v_mfma_f32_16x16x32_bf16 v[48:51], v[48:51], v[36:39], v[104:107]
	v_cvt_pk_bf16_f32 v101, v18, v19
	v_cndmask_b32_e64 v58, v58, 0, s[28:29]
	v_cndmask_b32_e64 v56, v56, 0, s[24:25]
	v_mfma_f32_16x16x32_bf16 v[60:63], v[60:63], v[36:39], v[142:145]
	ds_write_b64 v154, v[72:73]
	ds_write_b64 v154, v[74:75] offset:4352
	ds_write_b64 v98, v[100:101]
	ds_write_b64 v98, v[102:103] offset:4352
	s_waitcnt vmcnt(3)
; __device__ __forceinline__ unsigned cvtpk_s(float lo, float hi) { f32x2_t v = {lo, hi}; bf16x2_t b = __builtin_convertvector(v, bf16x2_t); return __builtin_bit_cast(unsigned, b); }
; #define HBAR() do { asm volatile("s_waitcnt lgkmcnt(0)" ::: "memory"); __builtin_amdgcn_s_barrier(); asm volatile("" ::: "memory"); } while (0)
; #define MFMA16(a, b, c) __builtin_amdgcn_mfma_f32_16x16x32_bf16((a), (b), (c), 0, 0, 0)
;     ...
;     for (int si = 0; si < 4; ++si)
; #pragma unroll
;         for (int j = 0; j < 4; ++j) if (16 * si + j > tq) as[si][j] = 0.f;
; #pragma unroll
;     for (int p = 0; p < 2; ++p) {
;         u32x4 pw; pw.x = cvtpk_s(as[2 * p][0], as[2 * p][1]); pw.y = cvtpk_s(as[2 * p][2], as[2 * p][3]); pw.z = cvtpk_s(as[2 * p + 1][0], as[2 * p + 1][1]); pw.w = cvtpk_s(as[2 * p + 1][2], as[2 * p + 1][3]);
; #pragma unroll
;         for (int vh = 0; vh < 2; ++vh) { const u32x4 vw = {va[vh][p].x, va[vh][p].y, vb2[vh][p].x, vb2[vh][p].y};
;             o[vh] = MFMA16(__builtin_bit_cast(bf16x8, pw), __builtin_bit_cast(bf16x8, vw), o[vh]); }
;     }
;     if ((VAR & 1) == 0 || o[0][0] == 12345.678f) {
; #pragma unroll
;     for (int vh = 0; vh < 2; ++vh)
; #pragma unroll
;         for (int j = 0; j < 4; ++j) *(bf16r*)(ob + (size_t)j * DM * 2 + vh * 32 + ol) = (bf16r)(cvtpk_s(o[vh][j], 0.f) & 0xffffu);
;     }
;     ...
;             if ((VAR & 4) == 0) hgM<1, VAR>(lds, st, ti, lane, ob + (size_t)(c + 1) * 64 * DM * 2, ol);
;             hgV<0>(lds, vA, mt); vA = *(const u32x4*)(vp + (size_t)(c + 4 < NC ? c + 4 : NC - 1) * 64 * DM);
;             HBAR();
	ds_write_b16 v135, v4 offset:53248
	ds_write_b16_d16_hi v135, v4 offset:53392
	ds_write_b16 v135, v5 offset:53536
	ds_write_b16_d16_hi v135, v5 offset:53680
	ds_write_b16 v135, v6 offset:53824
	v_mfma_f32_16x16x32_bf16 v[64:67], v[64:67], v[36:39], v[76:79]
	v_cndmask_b32_e64 v63, v63, 0, s[40:41]
	v_cndmask_b32_e64 v62, v62, 0, s[38:39]
	v_cndmask_b32_e64 v61, v61, 0, s[36:37]
	v_mfma_f32_16x16x32_bf16 v[36:39], v[44:47], v[36:39], v[68:71]
	v_cndmask_b32_e64 v47, v59, 0, s[30:31]
	v_cndmask_b32_e64 v46, v57, 0, s[26:27]
	v_cndmask_b32_e64 v45, v55, 0, s[22:23]
	v_cndmask_b32_e64 v44, v53, 0, s[16:17]
	v_cvt_pk_bf16_f32 v44, v52, v44
	v_cvt_pk_bf16_f32 v45, v54, v45
	v_cvt_pk_bf16_f32 v46, v56, v46
	v_cvt_pk_bf16_f32 v47, v58, v47
	v_cndmask_b32_e64 v4, v67, 0, s[14:15]
	v_cndmask_b32_e64 v5, v66, 0, s[46:47]
	v_cndmask_b32_e64 v65, v65, 0, s[44:45]
	v_cndmask_b32_e64 v64, v64, 0, s[42:43]
	v_cndmask_b32_e64 v60, v60, 0, s[34:35]
	v_mfma_f32_16x16x32_bf16 v[36:39], v[40:43], v[44:47], v[36:39]
	v_cvt_pk_bf16_f32 v40, v60, v61
	v_cvt_pk_bf16_f32 v41, v62, v63
	v_cvt_pk_bf16_f32 v42, v64, v65
	v_cvt_pk_bf16_f32 v43, v5, v4
	v_mfma_f32_16x16x32_bf16 v[32:35], v[32:35], v[44:47], v[48:51]
	ds_write_b16_d16_hi v135, v6 offset:53968
	ds_write_b16 v135, v7 offset:54112
	ds_write_b16_d16_hi v135, v7 offset:54256
	v_add_co_u32_e32 v148, vcc, s71, v92
	v_mfma_f32_16x16x32_bf16 v[28:31], v[28:31], v[40:43], v[36:39]
	s_lshl_b32 s48, s0, 18
	v_addc_co_u32_e32 v149, vcc, 0, v93, vcc
	v_mfma_f32_16x16x32_bf16 v[4:7], v[24:27], v[40:43], v[32:35]
	v_lshl_add_u64 v[152:153], v[90:91], 0, s[48:49]
	v_add_co_u32_e32 v152, vcc, 0x100000, v152
	s_nop 2
	v_cvt_pk_bf16_f32 v24, v28, v29
	v_addc_co_u32_e32 v153, vcc, 0, v153, vcc
	v_cvt_pk_bf16_f32 v25, v30, v31
	v_cvt_pk_bf16_f32 v26, v4, v5
	v_cvt_pk_bf16_f32 v27, v6, v7
	global_store_dwordx2 v[246:247], v[24:25], off
	global_store_dwordx2 v[246:247], v[26:27], off offset:32
	global_load_dwordx4 v[4:7], v[152:153], off
	s_waitcnt lgkmcnt(0)
	s_barrier
	s_sleep 10
	s_mov_b64 s[0:1], 0x80000
	s_cmpk_lt_u32 s3, 0x7e
	v_lshl_add_u64 v[92:93], v[92:93], 0, s[0:1]
	v_lshl_add_u64 v[244:245], v[244:245], 0, s[0:1]
	v_lshl_add_u64 v[246:247], v[246:247], 0, s[0:1]
	s_cbranch_scc1 .LBB0_1179
	s_mov_b64 s[16:17], 0
